# add: drop leader's final vmcnt(0) after the release atomics in the grid barrier
# baseline (speedup 1.0000x reference)
.LBB0_439:
	s_or_b64 exec, exec, s[4:5]
.LBB0_440:
	s_or_b64 exec, exec, s[0:1]
	s_mov_b32 s0, s55
	s_waitcnt lgkmcnt(0)
	s_barrier
	v_mbcnt_lo_u32_b32 v122, -1, 0
	v_mbcnt_hi_u32_b32 v122, -1, v122
	s_waitcnt vmcnt(22)
	v_mov_b32_e32 v6, 0
	s_waitcnt vmcnt(8)
	v_lshl_add_u32 v111, s0, 6, v122
	v_ashrrev_i32_e32 v3, 3, v111
	s_movk_i32 s0, 0x7f
	v_and_b32_e32 v4, 7, v122
	v_cmp_lt_i32_e32 vcc, s0, v3
	v_readlane_b32 s0, v255, 6
	v_lshlrev_b32_e32 v0, 4, v4
	v_readlane_b32 s1, v255, 7
	v_readfirstlane_b32 s20, v111
	v_mov_b32_e32 v2, 0
	v_lshl_add_u64 v[18:19], s[0:1], 0, v[0:1]
	s_xor_b64 s[0:1], s[84:85], -1
	s_or_b64 s[4:5], vcc, s[0:1]
	v_mov_b32_e32 v8, 0
	v_mov_b32_e32 v9, 0
	v_mov_b32_e32 v10, 0
	v_mov_b32_e32 v11, 0
	v_mov_b32_e32 v12, 0
	v_mov_b32_e32 v13, 0
	v_mov_b32_e32 v14, 0
	v_mov_b32_e32 v15, 0
	s_and_saveexec_b64 s[2:3], s[4:5]
	s_cbranch_execz .LBB0_442
	v_readlane_b32 s4, v255, 4
	s_nop 1
	v_add_u32_e32 v0, s4, v3
	s_movk_i32 s4, 0x3400
	v_mad_i64_i32 v[8:9], s[4:5], v0, s4, v[18:19]
	v_add_co_u32_e32 v8, vcc, 0x1000, v8
	s_nop 1
	v_addc_co_u32_e32 v9, vcc, 0, v9, vcc
	global_load_dwordx4 v[12:15], v[8:9], off
	s_nop 0
	global_load_dwordx4 v[8:11], v[8:9], off offset:512

.LBB0_716:
	s_or_b64 exec, exec, s[4:5]
.LBB0_717:
	v_writelane_b32 v254, s61, 16
	s_or_b64 exec, exec, s[0:1]
	s_add_u32 s20, s58, 0x3400000
	v_readlane_b32 s0, v254, 13
	s_addc_u32 s21, s0, 0
	v_readlane_b32 s0, v253, 45
	s_add_u32 s4, s20, s0
	v_readlane_b32 s0, v255, 61
	s_waitcnt lgkmcnt(0)
	s_barrier
	v_mbcnt_lo_u32_b32 v10, -1, 0
	v_mbcnt_hi_u32_b32 v10, -1, v10
	v_readlane_b32 s1, v253, 46
	v_lshl_add_u32 v0, s0, 6, v10
	v_ashrrev_i32_e32 v3, 31, v0
	v_lshrrev_b32_e32 v3, 26, v3
	v_readfirstlane_b32 s0, v0
	v_lshlrev_b32_e32 v2, 4, v0
	v_add_u32_e32 v3, v0, v3
	v_bfe_i32 v0, v0, 27, 1
	v_lshrrev_b32_e32 v0, 22, v0
	v_add_u32_e32 v0, v2, v0
	v_and_b32_e32 v0, 0xfffffc00, v0
	v_sub_u32_e32 v0, v2, v0
	v_ashrrev_i32_e32 v6, 6, v3
	v_lshrrev_b32_e32 v3, 4, v0
	v_bitop3_b32 v0, v3, v0, 32 bitop3:0x6c
	v_ashrrev_i32_e32 v4, 31, v0
	v_lshrrev_b32_e32 v4, 26, v4
	v_add_u32_e32 v4, v0, v4
	v_lshlrev_b32_e32 v3, 3, v6
	v_ashrrev_i32_e32 v7, 6, v4
	v_and_b32_e32 v4, 0xc0, v4
	v_and_b32_e32 v3, -16, v3
	v_sub_u32_e32 v0, v0, v4
	v_add_u32_e32 v3, v7, v3
	v_ashrrev_i16_sdwa v0, v210, sext(v0) dst_sel:DWORD dst_unused:UNUSED_PAD src0_sel:DWORD src1_sel:BYTE_0
	s_addc_u32 s5, s21, s1
	v_lshlrev_b32_e32 v5, 5, v6
	v_bfe_i32 v8, v0, 0, 16
	v_lshlrev_b32_e32 v0, 1, v3
	v_lshrrev_b32_e32 v4, 2, v3
	v_and_b32_e32 v9, 3, v7
	s_mov_b32 s1, 0x7ffe0
	v_and_b32_e32 v5, 32, v5
	v_and_b32_e32 v0, 24, v0
	v_and_b32_e32 v4, 4, v4
	v_and_or_b32 v9, v3, s1, v9
	v_or3_b32 v0, v9, v4, v0
	v_add_lshl_u32 v4, v5, v8, 1
	v_add_u32_e32 v2, 0x2000, v2
	v_lshl_add_u32 v134, v3, 13, v4
	v_ashrrev_i32_e32 v3, 31, v2
	v_lshrrev_b32_e32 v3, 22, v3
	v_add_u32_e32 v3, v2, v3
	v_ashrrev_i32_e32 v9, 10, v3
	v_mul_i32_i24_e32 v3, 0x400, v9
	v_sub_u32_e32 v2, v2, v3
	v_lshrrev_b32_e32 v3, 4, v2
	v_bitop3_b32 v2, v3, v2, 32 bitop3:0x6c
	v_lshl_add_u32 v0, v0, 13, v4
	v_ashrrev_i32_e32 v4, 31, v2
	v_lshrrev_b32_e32 v4, 26, v4
	v_lshlrev_b32_e32 v3, 3, v9
	v_add_u32_e32 v4, v2, v4
	v_and_b32_e32 v3, -16, v3
	v_ashrrev_i32_e32 v11, 6, v4
	v_and_b32_e32 v4, 0xc0, v4
	s_add_u32 s2, s4, 0x100000
	v_add_u32_e32 v3, v11, v3
	v_sub_u32_e32 v2, v2, v4
	v_and_b32_e32 v13, 3, v11
	s_addc_u32 s3, s5, 0
	v_ashrrev_i16_sdwa v2, v210, sext(v2) dst_sel:DWORD dst_unused:UNUSED_PAD src0_sel:DWORD src1_sel:BYTE_0
	v_and_or_b32 v13, v3, s1, v13
	s_ashr_i32 s1, s0, 6
	v_lshlrev_b32_e32 v5, 5, v9
	v_bfe_i32 v12, v2, 0, 16
	v_lshlrev_b32_e32 v2, 1, v3
	v_lshrrev_b32_e32 v4, 2, v3
	s_lshl_b32 s22, s1, 10
	v_and_b32_e32 v5, 32, v5
	v_and_b32_e32 v2, 24, v2
	v_and_b32_e32 v4, 4, v4
	s_add_i32 s23, s22, 0
	v_or3_b32 v2, v13, v4, v2
	v_add_lshl_u32 v4, v5, v12, 1
	s_add_i32 m0, s23, 0x10000
	v_lshl_add_u32 v138, v2, 13, v4
	global_load_lds_dwordx4 v0, s[4:5]
	s_add_i32 m0, s23, 0x12000
	s_add_i32 s24, s23, 0x2000
	global_load_lds_dwordx4 v138, s[4:5]
	s_add_i32 m0, s23, 0x14000
	v_lshl_add_u32 v136, v3, 13, v4
	global_load_lds_dwordx4 v0, s[2:3]
	s_add_i32 m0, s23, 0x16000
	s_add_i32 s25, s23, 0x4000
	global_load_lds_dwordx4 v138, s[2:3]
	v_readlane_b32 s2, v253, 47
	s_mov_b32 m0, s23
	v_readlane_b32 s3, v253, 48
	s_add_i32 s26, s23, 0x6000
	v_mov_b32_e32 v139, v1
	s_movk_i32 s55, 0x5600
	v_lshl_add_u64 v[2:3], s[4:5], 0, v[0:1]
	v_lshl_add_u64 v[4:5], s[4:5], 0, v[138:139]
	global_load_lds_dwordx4 v134, s[2:3]
	s_mov_b32 m0, s24
	s_nop 0
	global_load_lds_dwordx4 v136, s[2:3]
	v_readlane_b32 s2, v253, 49
	s_mov_b32 m0, s25
	v_readlane_b32 s3, v253, 50
	s_nop 4
	global_load_lds_dwordx4 v134, s[2:3]
	s_mov_b32 m0, s26
	s_nop 0
	global_load_lds_dwordx4 v136, s[2:3]
	s_ashr_i32 s2, s0, 8
	s_cmp_eq_u32 s2, 1
	s_cselect_b64 s[6:7], -1, 0
	s_cmp_lg_u32 s2, 1
	s_cbranch_scc1 .LBB0_719
	s_barrier

.LBB0_796:
	s_or_b64 exec, exec, s[4:5]
.LBB0_797:
	s_or_b64 exec, exec, s[0:1]
	v_readlane_b32 s0, v255, 61
	s_waitcnt lgkmcnt(0)
	s_barrier
	v_mbcnt_lo_u32_b32 v0, -1, 0
	v_mbcnt_hi_u32_b32 v0, -1, v0
	s_nop 0
	v_lshl_add_u32 v30, s0, 6, v0
	v_lshlrev_b32_e32 v28, 3, v30
	v_readlane_b32 s0, v254, 3
	v_ashrrev_i32_e32 v29, 31, v28
	v_readlane_b32 s1, v254, 4
	v_and_b32_e32 v202, 63, v0
	v_readfirstlane_b32 s6, v30
	v_lshl_add_u64 v[2:3], v[28:29], 0, s[0:1]
	v_readlane_b32 s0, v252, 50
	v_lshlrev_b64 v[2:3], 1, v[2:3]
	v_readlane_b32 s1, v252, 51
	s_nop 1
	v_lshl_add_u64 v[6:7], s[0:1], 0, v[2:3]
	v_readlane_b32 s0, v254, 5
	v_readlane_b32 s1, v254, 6
	global_load_dwordx4 v[32:35], v[6:7], off
	s_nop 0
	v_lshl_add_u64 v[26:27], s[0:1], 0, v[2:3]
	s_mov_b32 s0, 0x200000
	v_add_co_u32_e32 v8, vcc, s0, v6
	s_mov_b32 s0, 0x400000
	s_nop 0
	v_addc_co_u32_e32 v9, vcc, 0, v7, vcc
	global_load_dwordx4 v[36:39], v[8:9], off
	v_add_co_u32_e32 v8, vcc, s0, v6
	s_mov_b32 s0, 0x600000
	s_nop 0
	v_addc_co_u32_e32 v9, vcc, 0, v7, vcc
	global_load_dwordx4 v[2:5], v[26:27], off
	global_load_dwordx4 v[40:43], v[8:9], off
	v_add_co_u32_e32 v8, vcc, s0, v6
	s_mov_b32 s0, 0x800000
	s_nop 0
	v_addc_co_u32_e32 v9, vcc, 0, v7, vcc
	v_add_co_u32_e32 v10, vcc, s0, v6
	s_mov_b32 s0, 0xa00000
	s_nop 0
	v_addc_co_u32_e32 v11, vcc, 0, v7, vcc
	global_load_dwordx4 v[44:47], v[8:9], off
	global_load_dwordx4 v[48:51], v[10:11], off
	v_add_co_u32_e32 v8, vcc, s0, v6
	s_mov_b32 s0, 0xc00000
	s_nop 0
	v_addc_co_u32_e32 v9, vcc, 0, v7, vcc
	v_add_co_u32_e32 v10, vcc, s0, v6
	s_mov_b32 s0, 0xe00000
	s_nop 0
	v_addc_co_u32_e32 v11, vcc, 0, v7, vcc
	global_load_dwordx4 v[52:55], v[8:9], off
	global_load_dwordx4 v[56:59], v[10:11], off
	v_add_co_u32_e32 v8, vcc, s0, v6
	s_mov_b32 s0, 0x1000000
	s_nop 0
	v_addc_co_u32_e32 v9, vcc, 0, v7, vcc
	v_add_co_u32_e32 v10, vcc, s0, v6
	s_mov_b32 s0, 0x1200000
	s_nop 0
	v_addc_co_u32_e32 v11, vcc, 0, v7, vcc
	global_load_dwordx4 v[60:63], v[8:9], off
	global_load_dwordx4 v[64:67], v[10:11], off
	v_add_co_u32_e32 v8, vcc, s0, v6
	s_mov_b32 s0, 0x1400000
	s_nop 0
	v_addc_co_u32_e32 v9, vcc, 0, v7, vcc
	v_add_co_u32_e32 v10, vcc, s0, v6
	s_mov_b32 s0, 0x1600000
	s_nop 0
	v_addc_co_u32_e32 v11, vcc, 0, v7, vcc
	global_load_dwordx4 v[68:71], v[8:9], off
	global_load_dwordx4 v[72:75], v[10:11], off
	v_add_co_u32_e32 v8, vcc, s0, v6
	s_mov_b32 s0, 0x1800000
	s_nop 0
	v_addc_co_u32_e32 v9, vcc, 0, v7, vcc
	v_add_co_u32_e32 v10, vcc, s0, v6
	s_mov_b32 s0, 0x1a00000
	s_nop 0
	v_addc_co_u32_e32 v11, vcc, 0, v7, vcc
	global_load_dwordx4 v[22:25], v[8:9], off
	global_load_dwordx4 v[18:21], v[10:11], off
	v_add_co_u32_e32 v8, vcc, s0, v6
	s_mov_b32 s0, 0x1c00000
	s_nop 0
	v_addc_co_u32_e32 v9, vcc, 0, v7, vcc
	v_add_co_u32_e32 v10, vcc, s0, v6
	s_mov_b32 s0, 0x1e00000
	s_nop 0
	v_addc_co_u32_e32 v11, vcc, 0, v7, vcc
	global_load_dwordx4 v[14:17], v[8:9], off
	s_nop 0
	global_load_dwordx4 v[10:13], v[10:11], off
	v_add_co_u32_e32 v6, vcc, s0, v6
	s_waitcnt vmcnt(15)
	v_lshlrev_b32_e32 v76, 16, v32
	v_addc_co_u32_e32 v7, vcc, 0, v7, vcc
	global_load_dwordx4 v[6:9], v[6:7], off
	v_and_b32_e32 v77, 0xffff0000, v32
	v_lshlrev_b32_e32 v32, 16, v33
	v_and_b32_e32 v33, 0xffff0000, v33
	v_pk_add_f32 v[76:77], v[76:77], 0 op_sel_hi:[1,0]
	v_pk_add_f32 v[32:33], v[32:33], 0 op_sel_hi:[1,0]
	v_lshlrev_b32_e32 v78, 16, v34
	v_and_b32_e32 v79, 0xffff0000, v34
	v_lshlrev_b32_e32 v34, 16, v35
	v_and_b32_e32 v35, 0xffff0000, v35
	s_waitcnt vmcnt(15)
	v_lshlrev_b32_e32 v80, 16, v36
	v_and_b32_e32 v81, 0xffff0000, v36
	v_lshlrev_b32_e32 v36, 16, v37
	v_and_b32_e32 v37, 0xffff0000, v37
	v_pk_add_f32 v[78:79], v[78:79], 0 op_sel_hi:[1,0]
	v_pk_add_f32 v[34:35], v[34:35], 0 op_sel_hi:[1,0]
	v_pk_add_f32 v[32:33], v[32:33], v[36:37]
	v_pk_add_f32 v[36:37], v[76:77], v[80:81]
	v_lshlrev_b32_e32 v76, 16, v38
	v_and_b32_e32 v77, 0xffff0000, v38
	v_lshlrev_b32_e32 v38, 16, v39
	v_and_b32_e32 v39, 0xffff0000, v39
	v_pk_add_f32 v[34:35], v[34:35], v[38:39]
	v_pk_add_f32 v[38:39], v[78:79], v[76:77]
	s_waitcnt vmcnt(13)
	v_lshlrev_b32_e32 v76, 16, v40
	v_and_b32_e32 v77, 0xffff0000, v40
	v_lshlrev_b32_e32 v40, 16, v41
	v_and_b32_e32 v41, 0xffff0000, v41
	v_pk_add_f32 v[32:33], v[32:33], v[40:41]
	v_lshlrev_b32_e32 v40, 16, v42
	v_and_b32_e32 v41, 0xffff0000, v42
	v_pk_add_f32 v[36:37], v[36:37], v[76:77]
	v_lshlrev_b32_e32 v42, 16, v43
	v_and_b32_e32 v43, 0xffff0000, v43
	v_pk_add_f32 v[38:39], v[38:39], v[40:41]
	s_waitcnt vmcnt(12)
	v_lshlrev_b32_e32 v40, 16, v44
	v_and_b32_e32 v41, 0xffff0000, v44
	v_pk_add_f32 v[34:35], v[34:35], v[42:43]
	v_lshlrev_b32_e32 v42, 16, v45
	v_and_b32_e32 v43, 0xffff0000, v45
	v_pk_add_f32 v[36:37], v[36:37], v[40:41]
	v_lshlrev_b32_e32 v40, 16, v46
	v_and_b32_e32 v41, 0xffff0000, v46
	v_pk_add_f32 v[32:33], v[32:33], v[42:43]
	v_lshlrev_b32_e32 v42, 16, v47
	v_and_b32_e32 v43, 0xffff0000, v47
	v_pk_add_f32 v[38:39], v[38:39], v[40:41]
	s_waitcnt vmcnt(11)
	v_lshlrev_b32_e32 v40, 16, v48
	v_and_b32_e32 v41, 0xffff0000, v48
	v_pk_add_f32 v[34:35], v[34:35], v[42:43]
	v_lshlrev_b32_e32 v42, 16, v49
	v_and_b32_e32 v43, 0xffff0000, v49
	v_pk_add_f32 v[36:37], v[36:37], v[40:41]
	v_lshlrev_b32_e32 v40, 16, v50
	v_and_b32_e32 v41, 0xffff0000, v50
	v_pk_add_f32 v[32:33], v[32:33], v[42:43]
	v_lshlrev_b32_e32 v42, 16, v51
	v_and_b32_e32 v43, 0xffff0000, v51
	v_pk_add_f32 v[38:39], v[38:39], v[40:41]
	s_waitcnt vmcnt(10)
	v_lshlrev_b32_e32 v40, 16, v52
	v_and_b32_e32 v41, 0xffff0000, v52
	v_pk_add_f32 v[34:35], v[34:35], v[42:43]
	v_lshlrev_b32_e32 v42, 16, v53
	v_and_b32_e32 v43, 0xffff0000, v53
	v_pk_add_f32 v[36:37], v[36:37], v[40:41]
	v_lshlrev_b32_e32 v40, 16, v54
	v_and_b32_e32 v41, 0xffff0000, v54
	v_pk_add_f32 v[32:33], v[32:33], v[42:43]
	v_lshlrev_b32_e32 v42, 16, v55
	v_and_b32_e32 v43, 0xffff0000, v55
	v_pk_add_f32 v[38:39], v[38:39], v[40:41]
	s_waitcnt vmcnt(9)
	v_lshlrev_b32_e32 v40, 16, v56
	v_and_b32_e32 v41, 0xffff0000, v56
	v_pk_add_f32 v[34:35], v[34:35], v[42:43]
	v_lshlrev_b32_e32 v42, 16, v57
	v_and_b32_e32 v43, 0xffff0000, v57
	v_pk_add_f32 v[36:37], v[36:37], v[40:41]
	v_lshlrev_b32_e32 v40, 16, v58
	v_and_b32_e32 v41, 0xffff0000, v58
	v_pk_add_f32 v[32:33], v[32:33], v[42:43]
	v_lshlrev_b32_e32 v42, 16, v59
	v_and_b32_e32 v43, 0xffff0000, v59
	v_pk_add_f32 v[38:39], v[38:39], v[40:41]
	s_waitcnt vmcnt(8)
	v_lshlrev_b32_e32 v40, 16, v60
	v_and_b32_e32 v41, 0xffff0000, v60
	v_pk_add_f32 v[34:35], v[34:35], v[42:43]
	v_lshlrev_b32_e32 v42, 16, v61
	v_and_b32_e32 v43, 0xffff0000, v61
	v_pk_add_f32 v[36:37], v[36:37], v[40:41]
	v_lshlrev_b32_e32 v40, 16, v62
	v_and_b32_e32 v41, 0xffff0000, v62
	v_pk_add_f32 v[32:33], v[32:33], v[42:43]
	v_lshlrev_b32_e32 v42, 16, v63
	v_and_b32_e32 v43, 0xffff0000, v63
	v_pk_add_f32 v[38:39], v[38:39], v[40:41]
	s_waitcnt vmcnt(7)
	v_lshlrev_b32_e32 v40, 16, v64
	v_and_b32_e32 v41, 0xffff0000, v64
	v_pk_add_f32 v[34:35], v[34:35], v[42:43]
	v_lshlrev_b32_e32 v42, 16, v65
	v_and_b32_e32 v43, 0xffff0000, v65
	v_pk_add_f32 v[36:37], v[36:37], v[40:41]
	v_lshlrev_b32_e32 v40, 16, v66
	v_and_b32_e32 v41, 0xffff0000, v66
	v_pk_add_f32 v[32:33], v[32:33], v[42:43]
	v_lshlrev_b32_e32 v42, 16, v67
	v_and_b32_e32 v43, 0xffff0000, v67
	v_pk_add_f32 v[38:39], v[38:39], v[40:41]
	s_waitcnt vmcnt(6)
	v_lshlrev_b32_e32 v40, 16, v68
	v_and_b32_e32 v41, 0xffff0000, v68
	v_pk_add_f32 v[34:35], v[34:35], v[42:43]
	v_lshlrev_b32_e32 v42, 16, v69
	v_and_b32_e32 v43, 0xffff0000, v69
	v_pk_add_f32 v[36:37], v[36:37], v[40:41]
	v_lshlrev_b32_e32 v40, 16, v70
	v_and_b32_e32 v41, 0xffff0000, v70
	v_pk_add_f32 v[32:33], v[32:33], v[42:43]
	v_lshlrev_b32_e32 v42, 16, v71
	v_and_b32_e32 v43, 0xffff0000, v71
	v_pk_add_f32 v[38:39], v[38:39], v[40:41]
	s_waitcnt vmcnt(5)
	v_lshlrev_b32_e32 v40, 16, v72
	v_and_b32_e32 v41, 0xffff0000, v72
	v_pk_add_f32 v[34:35], v[34:35], v[42:43]
	v_lshlrev_b32_e32 v42, 16, v73
	v_and_b32_e32 v43, 0xffff0000, v73
	v_pk_add_f32 v[36:37], v[36:37], v[40:41]
	v_lshlrev_b32_e32 v40, 16, v74
	v_and_b32_e32 v41, 0xffff0000, v74
	v_pk_add_f32 v[32:33], v[32:33], v[42:43]
	v_lshlrev_b32_e32 v42, 16, v75
	v_and_b32_e32 v43, 0xffff0000, v75
	v_pk_add_f32 v[38:39], v[38:39], v[40:41]
	s_waitcnt vmcnt(4)
	v_lshlrev_b32_e32 v40, 16, v22
	v_and_b32_e32 v41, 0xffff0000, v22
	v_lshlrev_b32_e32 v22, 16, v23
	v_and_b32_e32 v23, 0xffff0000, v23
	v_pk_add_f32 v[34:35], v[34:35], v[42:43]
	v_pk_add_f32 v[22:23], v[32:33], v[22:23]
	v_pk_add_f32 v[32:33], v[36:37], v[40:41]
	v_lshlrev_b32_e32 v36, 16, v24
	v_and_b32_e32 v37, 0xffff0000, v24
	v_lshlrev_b32_e32 v24, 16, v25
	v_and_b32_e32 v25, 0xffff0000, v25
	v_pk_add_f32 v[24:25], v[34:35], v[24:25]
	v_pk_add_f32 v[34:35], v[38:39], v[36:37]
	s_waitcnt vmcnt(3)
	v_lshlrev_b32_e32 v36, 16, v18
	v_and_b32_e32 v37, 0xffff0000, v18
	v_lshlrev_b32_e32 v18, 16, v19
	v_and_b32_e32 v19, 0xffff0000, v19
	v_pk_add_f32 v[18:19], v[22:23], v[18:19]
	v_lshlrev_b32_e32 v22, 16, v20
	v_and_b32_e32 v23, 0xffff0000, v20
	v_lshlrev_b32_e32 v20, 16, v21
	v_and_b32_e32 v21, 0xffff0000, v21
	v_pk_add_f32 v[32:33], v[32:33], v[36:37]
	v_pk_add_f32 v[20:21], v[24:25], v[20:21]
	s_waitcnt vmcnt(2)
	v_lshlrev_b32_e32 v24, 16, v14
	v_and_b32_e32 v25, 0xffff0000, v14
	v_lshlrev_b32_e32 v14, 16, v15
	v_and_b32_e32 v15, 0xffff0000, v15
	v_pk_add_f32 v[22:23], v[34:35], v[22:23]
	v_pk_add_f32 v[14:15], v[18:19], v[14:15]
	v_pk_add_f32 v[18:19], v[32:33], v[24:25]
	v_lshlrev_b32_e32 v24, 16, v16
	v_and_b32_e32 v25, 0xffff0000, v16
	v_lshlrev_b32_e32 v16, 16, v17
	v_and_b32_e32 v17, 0xffff0000, v17
	v_pk_add_f32 v[16:17], v[20:21], v[16:17]
	v_pk_add_f32 v[20:21], v[22:23], v[24:25]
	s_waitcnt vmcnt(1)
	v_lshlrev_b32_e32 v22, 16, v10
	v_and_b32_e32 v23, 0xffff0000, v10
	v_lshlrev_b32_e32 v10, 16, v11
	v_and_b32_e32 v11, 0xffff0000, v11
	v_pk_add_f32 v[10:11], v[14:15], v[10:11]
	v_lshlrev_b32_e32 v14, 16, v12
	v_and_b32_e32 v15, 0xffff0000, v12
	v_lshlrev_b32_e32 v12, 16, v13
	v_and_b32_e32 v13, 0xffff0000, v13
	v_pk_add_f32 v[18:19], v[18:19], v[22:23]
	v_pk_add_f32 v[16:17], v[16:17], v[12:13]
	s_waitcnt vmcnt(0)
	v_lshlrev_b32_e32 v12, 16, v6
	v_and_b32_e32 v13, 0xffff0000, v6
	v_lshlrev_b32_e32 v6, 16, v7
	v_and_b32_e32 v7, 0xffff0000, v7
	v_pk_add_f32 v[14:15], v[20:21], v[14:15]
	v_pk_add_f32 v[10:11], v[10:11], v[6:7]
	v_pk_add_f32 v[12:13], v[18:19], v[12:13]
	v_lshlrev_b32_e32 v18, 16, v8
	v_and_b32_e32 v19, 0xffff0000, v8
	v_lshlrev_b32_e32 v6, 16, v9
	v_and_b32_e32 v7, 0xffff0000, v9
	v_pk_add_f32 v[8:9], v[14:15], v[18:19]
	v_mul_f32_e32 v14, v13, v13
	v_mul_f32_e32 v15, v11, v11
	v_fmac_f32_e32 v14, v12, v12
	v_fmac_f32_e32 v15, v10, v10
	v_add_f32_e32 v14, v14, v15
	v_mul_f32_e32 v15, v9, v9
	v_pk_add_f32 v[6:7], v[16:17], v[6:7]
	v_fmac_f32_e32 v15, v8, v8
	v_add_f32_e32 v14, v15, v14
	v_mul_f32_e32 v15, v7, v7
	v_fmac_f32_e32 v15, v6, v6
	v_add_f32_e32 v14, v15, v14
	ds_swizzle_b32 v15, v14 offset:swizzle(SWAP,1)
	v_ashrrev_i32_e32 v18, 6, v30
	v_cmp_eq_u32_e64 s[0:1], 0, v202
	s_waitcnt lgkmcnt(0)
	v_add_f32_e32 v14, v14, v15
	ds_swizzle_b32 v15, v14 offset:swizzle(SWAP,2)
	s_waitcnt lgkmcnt(0)
	v_add_f32_e32 v14, v14, v15
	ds_swizzle_b32 v15, v14 offset:swizzle(SWAP,4)
	s_waitcnt lgkmcnt(0)
	v_add_f32_e32 v14, v14, v15
	ds_swizzle_b32 v15, v14 offset:swizzle(SWAP,8)
	s_waitcnt lgkmcnt(0)
	v_add_f32_e32 v14, v14, v15
	ds_swizzle_b32 v15, v14 offset:swizzle(SWAP,16)
	s_waitcnt lgkmcnt(0)
	v_add_f32_e32 v0, v14, v15
	s_nop 0
	v_readlane_b32 s4, v0, 0
	v_readlane_b32 s5, v0, 32
	s_and_saveexec_b64 s[2:3], s[0:1]
	s_nop 0
	v_mov_b32_e32 v0, s5
	v_lshl_add_u32 v14, v18, 2, 0
	v_add_f32_e32 v0, s4, v0
	v_add_u32_e32 v14, 0x14000, v14
	ds_write_b32 v14, v0
	s_or_b64 exec, exec, s[2:3]
	v_mov_b32_e32 v0, s54
	s_waitcnt lgkmcnt(0)
	s_barrier
	ds_read_b128 v[20:23], v0
	s_lshl_b32 s86, s78, 12
	v_readlane_b32 s16, v252, 28
	s_lshl_b64 s[4:5], s[86:87], 2
	v_readlane_b32 s24, v252, 36
	s_add_u32 s2, s24, s4
	v_writelane_b32 v254, s4, 17
	s_waitcnt lgkmcnt(0)
	v_add_f32_e32 v0, 0, v20
	v_add_f32_e32 v0, v0, v21
	v_writelane_b32 v254, s5, 18
	v_readlane_b32 s4, v255, 42
	v_add_f32_e32 v0, v0, v22
	v_add_f32_e32 v0, v0, v23
	v_mov_b32_e32 v19, s4
	ds_read_b128 v[20:23], v19
	v_readlane_b32 s25, v252, 37
	s_addc_u32 s3, s25, s5
	v_lshl_add_u64 v[24:25], v[28:29], 2, s[2:3]
	v_lshlrev_b32_e32 v14, 16, v2
	s_waitcnt lgkmcnt(0)
	v_add_f32_e32 v0, v0, v20
	v_add_f32_e32 v0, v0, v21
	v_add_f32_e32 v0, v0, v22
	v_add_f32_e32 v0, v0, v23
	v_fmamk_f32 v0, v0, 0x39800000, v211
	v_cmp_gt_f32_e32 vcc, s94, v0
	v_mul_f32_e32 v19, 0x4f800000, v0
	v_and_b32_e32 v15, 0xffff0000, v2
	v_cndmask_b32_e32 v0, v0, v19, vcc
	v_sqrt_f32_e32 v19, v0
	v_lshlrev_b32_e32 v16, 16, v3
	v_and_b32_e32 v17, 0xffff0000, v3
	v_lshlrev_b32_e32 v2, 16, v4
	v_add_u32_e32 v20, -1, v19
	v_fma_f32 v21, -v20, v19, v0
	v_cmp_ge_f32_e64 s[4:5], 0, v21
	v_add_u32_e32 v21, 1, v19
	v_and_b32_e32 v3, 0xffff0000, v4
	v_cndmask_b32_e64 v20, v19, v20, s[4:5]
	v_fma_f32 v19, -v21, v19, v0
	v_cmp_lt_f32_e64 s[4:5], 0, v19
	v_lshlrev_b32_e32 v4, 16, v5
	v_and_b32_e32 v5, 0xffff0000, v5
	v_cndmask_b32_e64 v19, v20, v21, s[4:5]
	v_mul_f32_e32 v20, 0x37800000, v19
	v_cndmask_b32_e32 v19, v19, v20, vcc
	v_cmp_class_f32_e32 vcc, v0, v212
	v_readlane_b32 s17, v252, 29
	v_readlane_b32 s18, v252, 30
	v_cndmask_b32_e32 v0, v19, v0, vcc
	v_div_scale_f32 v19, s[4:5], v0, v0, 1.0
	v_rcp_f32_e32 v20, v19
	v_readlane_b32 s19, v252, 31
	v_readlane_b32 s20, v252, 32
	v_readlane_b32 s21, v252, 33
	v_fma_f32 v21, -v19, v20, 1.0
	v_fmac_f32_e32 v20, v21, v20
	v_div_scale_f32 v21, vcc, 1.0, v0, 1.0
	v_mul_f32_e32 v22, v21, v20
	v_fma_f32 v23, -v19, v22, v21
	v_fmac_f32_e32 v22, v23, v20
	v_fma_f32 v19, -v19, v22, v21
	v_div_fmas_f32 v19, v19, v20, v22
	global_load_dwordx4 v[20:23], v[24:25], off offset:16
	global_load_dwordx4 v[32:35], v[24:25], off
	v_div_fixup_f32 v0, v19, v0, 1.0
	v_pk_mul_f32 v[12:13], v[12:13], v[0:1] op_sel_hi:[1,0]
	v_pk_mul_f32 v[10:11], v[10:11], v[0:1] op_sel_hi:[1,0]
	v_pk_mul_f32 v[8:9], v[8:9], v[0:1] op_sel_hi:[1,0]
	v_pk_mul_f32 v[6:7], v[6:7], v[0:1] op_sel_hi:[1,0]
	v_readlane_b32 s22, v252, 34
	v_readlane_b32 s23, v252, 35
	v_readlane_b32 s26, v252, 38
	v_readlane_b32 s27, v252, 39
	v_readlane_b32 s28, v252, 40
	v_readlane_b32 s29, v252, 41
	v_readlane_b32 s30, v252, 42
	v_readlane_b32 s31, v252, 43
	s_waitcnt vmcnt(1)
	v_pk_fma_f32 v[8:9], v[20:21], v[8:9], v[2:3]
	s_waitcnt vmcnt(0)
	v_pk_fma_f32 v[10:11], v[34:35], v[10:11], v[16:17]
	v_pk_fma_f32 v[12:13], v[32:33], v[12:13], v[14:15]
	v_pk_fma_f32 v[6:7], v[22:23], v[6:7], v[4:5]
	v_cvt_pk_bf16_f32 v2, v12, v13
	v_cvt_pk_bf16_f32 v3, v10, v11
	v_cvt_pk_bf16_f32 v4, v8, v9
	v_mul_f32_e32 v0, v13, v13
	v_cvt_pk_bf16_f32 v5, v6, v7
	global_store_dwordx4 v[26:27], v[2:5], off
	v_fmac_f32_e32 v0, v12, v12
	s_nop 0
	v_mul_f32_e32 v2, v11, v11
	v_fmac_f32_e32 v2, v10, v10
	v_add_f32_e32 v0, v0, v2
	v_mul_f32_e32 v2, v9, v9
	v_fmac_f32_e32 v2, v8, v8
	v_add_f32_e32 v0, v2, v0
	v_mul_f32_e32 v2, v7, v7
	v_fmac_f32_e32 v2, v6, v6
	v_add_f32_e32 v0, v2, v0
	ds_swizzle_b32 v2, v0 offset:swizzle(SWAP,1)
	s_waitcnt lgkmcnt(0)
	v_add_f32_e32 v0, v0, v2
	ds_swizzle_b32 v2, v0 offset:swizzle(SWAP,2)
	s_waitcnt lgkmcnt(0)
	v_add_f32_e32 v0, v0, v2
	ds_swizzle_b32 v2, v0 offset:swizzle(SWAP,4)
	s_waitcnt lgkmcnt(0)
	v_add_f32_e32 v0, v0, v2
	ds_swizzle_b32 v2, v0 offset:swizzle(SWAP,8)
	s_waitcnt lgkmcnt(0)
	v_add_f32_e32 v0, v0, v2
	ds_swizzle_b32 v2, v0 offset:swizzle(SWAP,16)
	s_waitcnt lgkmcnt(0)
	v_add_f32_e32 v0, v0, v2
	s_nop 0
	v_readlane_b32 s7, v0, 0
	v_readlane_b32 s8, v0, 32
	s_and_saveexec_b64 s[4:5], s[0:1]
	s_nop 0
	v_mov_b32_e32 v0, s8
	v_add_f32_e32 v0, s7, v0
	v_lshl_add_u32 v2, v18, 2, s54
	ds_write_b32 v2, v0 offset:32
	s_or_b64 exec, exec, s[4:5]
	v_cmp_eq_u32_e32 vcc, 0, v30
	s_waitcnt lgkmcnt(0)
	s_barrier
	s_and_saveexec_b64 s[4:5], vcc
	s_cbranch_execz .LBB0_803
	v_readlane_b32 s0, v255, 43
	s_nop 1
	v_mov_b32_e32 v0, s0
	ds_read_b128 v[2:5], v0
	v_readlane_b32 s0, v255, 44
	s_waitcnt lgkmcnt(0)
	v_add_f32_e32 v0, 0, v2
	v_add_f32_e32 v0, v0, v3
	v_add_f32_e32 v0, v0, v4
	v_mov_b32_e32 v2, s0
	v_add_f32_e32 v0, v0, v5
	ds_read_b128 v[2:5], v2
	s_waitcnt lgkmcnt(0)
	v_add_f32_e32 v0, v0, v2
	v_add_f32_e32 v0, v0, v3
	v_add_f32_e32 v0, v0, v4
	v_add_f32_e32 v0, v0, v5
	v_fmamk_f32 v0, v0, 0x39800000, v211
	v_cmp_gt_f32_e32 vcc, s94, v0
	v_mul_f32_e32 v2, 0x4f800000, v0
	s_nop 0
	v_cndmask_b32_e32 v0, v0, v2, vcc
	v_sqrt_f32_e32 v2, v0
	s_nop 0
	v_add_u32_e32 v3, -1, v2
	v_fma_f32 v4, -v3, v2, v0
	v_cmp_ge_f32_e64 s[0:1], 0, v4
	v_add_u32_e32 v4, 1, v2
	s_nop 0
	v_cndmask_b32_e64 v3, v2, v3, s[0:1]
	v_fma_f32 v2, -v4, v2, v0
	v_cmp_lt_f32_e64 s[0:1], 0, v2
	s_nop 1
	v_cndmask_b32_e64 v2, v3, v4, s[0:1]
	v_mul_f32_e32 v3, 0x37800000, v2
	v_cndmask_b32_e32 v2, v2, v3, vcc
	v_cmp_class_f32_e32 vcc, v0, v212
	s_nop 1
	v_cndmask_b32_e32 v0, v2, v0, vcc
	v_div_scale_f32 v2, s[0:1], v0, v0, 1.0
	v_rcp_f32_e32 v3, v2
	v_readlane_b32 s0, v254, 9
	v_readlane_b32 s1, v254, 10
	v_fma_f32 v4, -v2, v3, 1.0
	v_fmac_f32_e32 v3, v4, v3
	v_div_scale_f32 v4, vcc, 1.0, v0, 1.0
	v_mul_f32_e32 v5, v4, v3
	v_fma_f32 v6, -v2, v5, v4
	v_fmac_f32_e32 v5, v6, v3
	v_fma_f32 v2, -v2, v5, v4
	v_div_fmas_f32 v2, v2, v3, v5
	v_div_fixup_f32 v0, v2, v0, 1.0
	global_store_dword v1, v0, s[0:1]

.LBB0_858:
	s_or_b64 exec, exec, s[4:5]
.LBB0_859:
	s_or_b64 exec, exec, s[0:1]
	s_add_u32 s20, s58, 0x5400000
	v_readlane_b32 s0, v254, 13
	v_readlane_b32 s24, v252, 4
	s_addc_u32 s21, s0, 0
	s_mul_i32 s0, s78, 0x20400
	v_readlane_b32 s28, v252, 8
	v_readlane_b32 s29, v252, 9
	s_add_u32 s10, s28, s0
	v_readlane_b32 s30, v252, 10
	s_addc_u32 s11, s29, 0
	s_mul_i32 s0, s78, 0xac00
	v_readlane_b32 s31, v252, 11
	s_add_u32 s12, s30, s0
	s_mul_i32 s86, s78, 0xac000
	v_readlane_b32 s36, v252, 12
	s_addc_u32 s13, s31, 0
	s_lshl_b64 s[0:1], s[86:87], 2
	v_readlane_b32 s44, v252, 20
	v_readlane_b32 s45, v252, 21
	s_add_u32 s18, s44, s0
	s_addc_u32 s19, s45, s1
	s_mul_i32 s2, s78, 0x56000
	v_readlane_b32 s3, v253, 53
	s_add_u32 s22, s3, s2
	v_readlane_b32 s2, v253, 54
	s_addc_u32 s23, s2, 0
	v_readlane_b32 s2, v253, 55
	s_add_u32 s64, s2, s0
	v_readlane_b32 s0, v253, 56
	s_addc_u32 s65, s0, s1
	v_readlane_b32 s0, v252, 0
	s_add_u32 s16, s10, 0x15800
	v_readlane_b32 s1, v252, 1
	s_addc_u32 s17, s11, 0
	v_readlane_b32 s2, v252, 2
	v_readlane_b32 s0, v254, 14
	v_readlane_b32 s3, v252, 3
	v_readlane_b32 s1, v254, 15
	s_add_u32 s44, s2, s0
	v_readlane_b32 s46, v252, 22
	s_addc_u32 s45, s3, s1
	v_readlane_b32 s26, v252, 6
	v_readlane_b32 s27, v252, 7
	v_readlane_b32 s47, v252, 23
	s_add_u32 s46, s44, 0x9100
	v_readlane_b32 s0, v253, 34
	s_addc_u32 s47, s45, 0
	s_mov_b32 s27, 11
	s_mov_b32 s28, 0
	s_mov_b32 s26, s0
	s_waitcnt lgkmcnt(0)
	s_barrier
	v_readlane_b32 s25, v252, 5
	v_readlane_b32 s37, v252, 13
	v_readlane_b32 s38, v252, 14
	v_readlane_b32 s39, v252, 15
	v_readlane_b32 s40, v252, 16
	v_readlane_b32 s41, v252, 17
	v_readlane_b32 s42, v252, 18
	v_readlane_b32 s43, v252, 19
	v_readlane_b32 s48, v252, 24
	v_readlane_b32 s49, v252, 25
	v_readlane_b32 s50, v252, 26
	v_readlane_b32 s51, v252, 27
	v_readlane_b32 s1, v253, 35
	s_branch .LBB0_862

.LBB0_1094:
	s_or_b64 exec, exec, s[4:5]
.LBB0_1095:
	s_or_b64 exec, exec, s[0:1]
	s_mov_b32 s0, s55
	s_waitcnt lgkmcnt(0)
	s_barrier
	s_lshl_b32 s0, s0, 6
	v_readlane_b32 s1, v253, 37
	v_mbcnt_lo_u32_b32 v0, -1, 0
	v_mbcnt_hi_u32_b32 v0, -1, v0
	s_add_i32 s0, s0, s1
	v_add_u32_e32 v0, s0, v0
	s_mov_b32 s0, 0x2b000
	v_cmp_gt_i32_e32 vcc, s0, v0
	s_and_saveexec_b64 s[0:1], vcc
	s_cbranch_execz .LBB0_1100
	s_add_u32 s4, s10, 0xac00
	s_addc_u32 s5, s11, 0
	s_mov_b64 s[6:7], 0
	s_branch .LBB0_1098

.LBB0_1151:
	s_or_b64 exec, exec, s[4:5]
.LBB0_1152:
	s_or_b64 exec, exec, s[0:1]
	s_mov_b32 s2, s55
	s_waitcnt lgkmcnt(0)
	s_barrier
	s_waitcnt vmcnt(21)
	v_mbcnt_lo_u32_b32 v11, -1, 0
	v_mbcnt_hi_u32_b32 v11, -1, v11
	s_mov_b32 s6, 0xffffe0
	v_lshl_add_u32 v0, s2, 6, v11
	v_ashrrev_i32_e32 v3, 31, v0
	v_lshrrev_b32_e32 v3, 26, v3
	v_readfirstlane_b32 s2, v0
	v_lshlrev_b32_e32 v2, 4, v0
	v_add_u32_e32 v3, v0, v3
	v_bfe_i32 v0, v0, 27, 1
	v_lshrrev_b32_e32 v0, 22, v0
	v_add_u32_e32 v0, v2, v0
	v_and_b32_e32 v0, 0xfffffc00, v0
	v_sub_u32_e32 v0, v2, v0
	v_ashrrev_i32_e32 v6, 6, v3
	v_lshrrev_b32_e32 v3, 4, v0
	v_bitop3_b32 v0, v3, v0, 32 bitop3:0x6c
	v_ashrrev_i32_e32 v4, 31, v0
	v_lshrrev_b32_e32 v4, 26, v4
	v_lshlrev_b32_e32 v3, 3, v6
	v_add_u32_e32 v4, v0, v4
	v_and_b32_e32 v3, -16, v3
	v_ashrrev_i32_e32 v8, 6, v4
	v_and_b32_e32 v4, 0xc0, v4
	v_add_u32_e32 v3, v8, v3
	v_lshlrev_b32_e32 v5, 5, v6
	v_sub_u32_e32 v0, v0, v4
	v_and_b32_e32 v7, 32, v5
	v_ashrrev_i16_sdwa v0, v210, sext(v0) dst_sel:DWORD dst_unused:UNUSED_PAD src0_sel:DWORD src1_sel:BYTE_0
	v_lshlrev_b32_e32 v4, 1, v3
	v_lshrrev_b32_e32 v5, 2, v3
	v_and_b32_e32 v10, 3, v8
	v_bfe_i32 v9, v0, 0, 16
	v_and_b32_e32 v4, 24, v4
	v_and_b32_e32 v5, 4, v5
	v_and_or_b32 v10, v3, s6, v10
	s_movk_i32 s3, 0x2b00
	v_add_u32_e32 v0, v7, v9
	v_or3_b32 v4, v10, v5, v4
	v_mul_lo_u32 v3, v3, s3
	v_add_lshl_u32 v134, v0, v3, 1
	v_mul_u32_u24_e32 v3, 0x2b00, v4
	v_add_u32_e32 v2, 0x2000, v2
	v_add_lshl_u32 v0, v3, v0, 1
	v_ashrrev_i32_e32 v3, 31, v2
	v_lshrrev_b32_e32 v3, 22, v3
	v_add_u32_e32 v3, v2, v3
	v_ashrrev_i32_e32 v10, 10, v3
	v_mul_i32_i24_e32 v3, 0x400, v10
	v_sub_u32_e32 v2, v2, v3
	v_lshrrev_b32_e32 v3, 4, v2
	v_bitop3_b32 v2, v3, v2, 32 bitop3:0x6c
	s_add_u32 s20, s58, 0x10000000
	v_readlane_b32 s0, v254, 13
	v_readlane_b32 s1, v253, 42
	v_ashrrev_i32_e32 v4, 31, v2
	s_addc_u32 s21, s0, 0
	s_mul_i32 s0, s1, 0x560000
	v_lshrrev_b32_e32 v4, 26, v4
	s_add_u32 s4, s20, s0
	s_mul_hi_i32 s0, s1, 0x560000
	v_lshlrev_b32_e32 v3, 3, v10
	v_add_u32_e32 v4, v2, v4
	s_addc_u32 s5, s21, s0
	v_and_b32_e32 v3, -16, v3
	v_ashrrev_i32_e32 v13, 6, v4
	v_and_b32_e32 v4, 0xc0, v4
	s_add_u32 s0, s4, 0x2b0000
	v_add_u32_e32 v3, v13, v3
	v_lshlrev_b32_e32 v5, 5, v10
	v_sub_u32_e32 v2, v2, v4
	s_waitcnt vmcnt(20)
	v_and_b32_e32 v15, 3, v13
	s_addc_u32 s1, s5, 0
	v_and_b32_e32 v12, 32, v5
	v_ashrrev_i16_sdwa v2, v210, sext(v2) dst_sel:DWORD dst_unused:UNUSED_PAD src0_sel:DWORD src1_sel:BYTE_0
	v_lshlrev_b32_e32 v4, 1, v3
	v_lshrrev_b32_e32 v5, 2, v3
	v_and_or_b32 v15, v3, s6, v15
	v_mul_lo_u32 v3, v3, s3
	s_ashr_i32 s3, s2, 6
	v_bfe_i32 v14, v2, 0, 16
	v_and_b32_e32 v4, 24, v4
	v_and_b32_e32 v5, 4, v5
	s_lshl_b32 s22, s3, 10
	v_add_u32_e32 v2, v12, v14
	v_or3_b32 v4, v15, v5, v4
	s_add_i32 s23, s22, 0
	v_add_lshl_u32 v136, v2, v3, 1
	v_mul_u32_u24_e32 v3, 0x2b00, v4
	s_add_i32 m0, s23, 0x10000
	v_add_lshl_u32 v138, v3, v2, 1
	global_load_lds_dwordx4 v0, s[4:5]
	s_add_i32 m0, s23, 0x12000
	s_add_i32 s24, s23, 0x2000
	global_load_lds_dwordx4 v138, s[4:5]
	s_add_i32 m0, s23, 0x14000
	s_add_i32 s25, s23, 0x4000
	global_load_lds_dwordx4 v0, s[0:1]
	s_add_i32 m0, s23, 0x16000
	s_add_i32 s26, s23, 0x6000
	global_load_lds_dwordx4 v138, s[0:1]
	v_readlane_b32 s0, v253, 59
	s_mov_b32 m0, s23
	v_readlane_b32 s1, v253, 60
	v_mov_b32_e32 v139, v1
	v_lshl_add_u64 v[2:3], s[4:5], 0, v[0:1]
	v_lshl_add_u64 v[4:5], s[4:5], 0, v[138:139]
	s_nop 1
	global_load_lds_dwordx4 v134, s[0:1]
	s_mov_b32 m0, s24
	s_nop 0
	global_load_lds_dwordx4 v136, s[0:1]
	v_readlane_b32 s0, v253, 61
	s_mov_b32 m0, s25
	v_readlane_b32 s1, v253, 62
	s_nop 4
	global_load_lds_dwordx4 v134, s[0:1]
	s_mov_b32 m0, s26
	s_nop 0
	global_load_lds_dwordx4 v136, s[0:1]
	s_ashr_i32 s0, s2, 8
	s_cmp_eq_u32 s0, 1
	s_cselect_b64 s[6:7], -1, 0
	s_cmp_lg_u32 s0, 1
	s_cbranch_scc1 .LBB0_1154
	s_barrier

.LBB0_1231:
	s_or_b64 exec, exec, s[4:5]
.LBB0_1232:
	s_or_b64 exec, exec, s[0:1]
	s_mov_b32 s0, s55
	s_waitcnt lgkmcnt(0)
	s_barrier
	v_mbcnt_lo_u32_b32 v0, -1, 0
	v_mbcnt_hi_u32_b32 v0, -1, v0
	s_mov_b64 s[2:3], -1
	v_lshl_add_u32 v205, s0, 6, v0
	v_and_b32_e32 v204, 63, v0
	v_readfirstlane_b32 s0, v205
	s_ashr_i32 s6, s0, 6
	v_readlane_b32 s0, v254, 11
	v_readlane_b32 s1, v254, 12
	v_lshlrev_b32_e32 v66, 3, v205
	s_andn2_b64 vcc, exec, s[0:1]
	v_cmp_eq_u32_e64 s[0:1], 0, v204
	v_ashrrev_i32_e32 v67, 31, v66
	s_cbranch_vccnz .LBB0_1244
	v_readlane_b32 s2, v254, 3
	v_readlane_b32 s3, v254, 4
	s_nop 1
	v_lshl_add_u64 v[2:3], v[66:67], 0, s[2:3]
	v_readlane_b32 s2, v254, 5
	v_lshlrev_b64 v[2:3], 1, v[2:3]
	v_readlane_b32 s3, v254, 6
	s_nop 1
	v_lshl_add_u64 v[30:31], s[2:3], 0, v[2:3]
	v_readlane_b32 s2, v252, 50
	v_readlane_b32 s3, v252, 51
	s_nop 1
	v_lshl_add_u64 v[6:7], s[2:3], 0, v[2:3]
	v_add_co_u32_e32 v8, vcc, 0x200000, v6
	global_load_dwordx4 v[2:5], v[30:31], off
	global_load_dwordx4 v[32:35], v[6:7], off
	v_addc_co_u32_e32 v9, vcc, 0, v7, vcc
	v_add_co_u32_e32 v10, vcc, 0x400000, v6
	s_waitcnt vmcnt(0)
	v_lshlrev_b32_e32 v64, 16, v32
	v_addc_co_u32_e32 v11, vcc, 0, v7, vcc
	global_load_dwordx4 v[36:39], v[8:9], off
	global_load_dwordx4 v[40:43], v[10:11], off
	v_add_co_u32_e32 v8, vcc, 0x600000, v6
	v_and_b32_e32 v65, 0xffff0000, v32
	s_nop 0
	v_addc_co_u32_e32 v9, vcc, 0, v7, vcc
	v_add_co_u32_e32 v10, vcc, 0x800000, v6
	v_lshlrev_b32_e32 v32, 16, v33
	s_nop 0
	v_addc_co_u32_e32 v11, vcc, 0, v7, vcc
	global_load_dwordx4 v[44:47], v[8:9], off
	global_load_dwordx4 v[48:51], v[10:11], off
	v_add_co_u32_e32 v8, vcc, 0xa00000, v6
	v_and_b32_e32 v33, 0xffff0000, v33
	s_nop 0
	v_addc_co_u32_e32 v9, vcc, 0, v7, vcc
	v_add_co_u32_e32 v10, vcc, 0xc00000, v6
	v_pk_add_f32 v[64:65], v[64:65], 0 op_sel_hi:[1,0]
	s_nop 0
	v_addc_co_u32_e32 v11, vcc, 0, v7, vcc
	global_load_dwordx4 v[52:55], v[8:9], off
	global_load_dwordx4 v[56:59], v[10:11], off
	v_add_co_u32_e32 v8, vcc, 0xe00000, v6
	v_pk_add_f32 v[32:33], v[32:33], 0 op_sel_hi:[1,0]
	s_nop 0
	v_addc_co_u32_e32 v9, vcc, 0, v7, vcc
	v_add_co_u32_e32 v10, vcc, 0x1000000, v6
	v_lshlrev_b32_e32 v76, 16, v34
	s_nop 0
	v_addc_co_u32_e32 v11, vcc, 0, v7, vcc
	global_load_dwordx4 v[60:63], v[8:9], off
	global_load_dwordx4 v[68:71], v[10:11], off
	v_add_co_u32_e32 v8, vcc, 0x1200000, v6
	v_and_b32_e32 v77, 0xffff0000, v34
	s_nop 0
	v_addc_co_u32_e32 v9, vcc, 0, v7, vcc
	v_add_co_u32_e32 v10, vcc, 0x1400000, v6
	v_lshlrev_b32_e32 v34, 16, v35
	s_nop 0
	v_addc_co_u32_e32 v11, vcc, 0, v7, vcc
	global_load_dwordx4 v[72:75], v[8:9], off
	global_load_dwordx4 v[26:29], v[10:11], off
	v_add_co_u32_e32 v8, vcc, 0x1600000, v6
	v_and_b32_e32 v35, 0xffff0000, v35
	s_nop 0
	v_addc_co_u32_e32 v9, vcc, 0, v7, vcc
	v_add_co_u32_e32 v10, vcc, 0x1800000, v6
	v_pk_add_f32 v[76:77], v[76:77], 0 op_sel_hi:[1,0]
	s_nop 0
	v_addc_co_u32_e32 v11, vcc, 0, v7, vcc
	global_load_dwordx4 v[22:25], v[8:9], off
	global_load_dwordx4 v[18:21], v[10:11], off
	v_add_co_u32_e32 v8, vcc, 0x1a00000, v6
	v_pk_add_f32 v[34:35], v[34:35], 0 op_sel_hi:[1,0]
	s_nop 0
	v_addc_co_u32_e32 v9, vcc, 0, v7, vcc
	v_add_co_u32_e32 v10, vcc, 0x1c00000, v6
	s_waitcnt vmcnt(11)
	v_lshlrev_b32_e32 v78, 16, v36
	v_addc_co_u32_e32 v11, vcc, 0, v7, vcc
	global_load_dwordx4 v[14:17], v[8:9], off
	s_nop 0
	global_load_dwordx4 v[10:13], v[10:11], off
	v_add_co_u32_e32 v6, vcc, 0x1e00000, v6
	v_and_b32_e32 v79, 0xffff0000, v36
	s_nop 0
	v_addc_co_u32_e32 v7, vcc, 0, v7, vcc
	global_load_dwordx4 v[6:9], v[6:7], off
	v_lshlrev_b32_e32 v36, 16, v37
	v_and_b32_e32 v37, 0xffff0000, v37
	v_pk_add_f32 v[32:33], v[32:33], v[36:37]
	v_pk_add_f32 v[36:37], v[64:65], v[78:79]
	v_lshlrev_b32_e32 v64, 16, v38
	v_and_b32_e32 v65, 0xffff0000, v38
	v_lshlrev_b32_e32 v38, 16, v39
	v_and_b32_e32 v39, 0xffff0000, v39
	v_pk_add_f32 v[34:35], v[34:35], v[38:39]
	v_pk_add_f32 v[38:39], v[76:77], v[64:65]
	s_waitcnt vmcnt(13)
	v_lshlrev_b32_e32 v64, 16, v40
	v_and_b32_e32 v65, 0xffff0000, v40
	v_lshlrev_b32_e32 v40, 16, v41
	v_and_b32_e32 v41, 0xffff0000, v41
	v_pk_add_f32 v[32:33], v[32:33], v[40:41]
	v_lshlrev_b32_e32 v40, 16, v42
	v_and_b32_e32 v41, 0xffff0000, v42
	v_pk_add_f32 v[36:37], v[36:37], v[64:65]
	v_lshlrev_b32_e32 v42, 16, v43
	v_and_b32_e32 v43, 0xffff0000, v43
	v_pk_add_f32 v[38:39], v[38:39], v[40:41]
	s_waitcnt vmcnt(12)
	v_lshlrev_b32_e32 v40, 16, v44
	v_and_b32_e32 v41, 0xffff0000, v44
	v_pk_add_f32 v[34:35], v[34:35], v[42:43]
	v_lshlrev_b32_e32 v42, 16, v45
	v_and_b32_e32 v43, 0xffff0000, v45
	v_pk_add_f32 v[36:37], v[36:37], v[40:41]
	v_lshlrev_b32_e32 v40, 16, v46
	v_and_b32_e32 v41, 0xffff0000, v46
	v_pk_add_f32 v[32:33], v[32:33], v[42:43]
	v_lshlrev_b32_e32 v42, 16, v47
	v_and_b32_e32 v43, 0xffff0000, v47
	v_pk_add_f32 v[38:39], v[38:39], v[40:41]
	s_waitcnt vmcnt(11)
	v_lshlrev_b32_e32 v40, 16, v48
	v_and_b32_e32 v41, 0xffff0000, v48
	v_pk_add_f32 v[34:35], v[34:35], v[42:43]
	v_lshlrev_b32_e32 v42, 16, v49
	v_and_b32_e32 v43, 0xffff0000, v49
	v_pk_add_f32 v[36:37], v[36:37], v[40:41]
	v_lshlrev_b32_e32 v40, 16, v50
	v_and_b32_e32 v41, 0xffff0000, v50
	v_pk_add_f32 v[32:33], v[32:33], v[42:43]
	v_lshlrev_b32_e32 v42, 16, v51
	v_and_b32_e32 v43, 0xffff0000, v51
	v_pk_add_f32 v[38:39], v[38:39], v[40:41]
	s_waitcnt vmcnt(10)
	v_lshlrev_b32_e32 v40, 16, v52
	v_and_b32_e32 v41, 0xffff0000, v52
	v_pk_add_f32 v[34:35], v[34:35], v[42:43]
	v_lshlrev_b32_e32 v42, 16, v53
	v_and_b32_e32 v43, 0xffff0000, v53
	v_pk_add_f32 v[36:37], v[36:37], v[40:41]
	v_lshlrev_b32_e32 v40, 16, v54
	v_and_b32_e32 v41, 0xffff0000, v54
	v_pk_add_f32 v[32:33], v[32:33], v[42:43]
	v_lshlrev_b32_e32 v42, 16, v55
	v_and_b32_e32 v43, 0xffff0000, v55
	v_pk_add_f32 v[38:39], v[38:39], v[40:41]
	s_waitcnt vmcnt(9)
	v_lshlrev_b32_e32 v40, 16, v56
	v_and_b32_e32 v41, 0xffff0000, v56
	v_pk_add_f32 v[34:35], v[34:35], v[42:43]
	v_lshlrev_b32_e32 v42, 16, v57
	v_and_b32_e32 v43, 0xffff0000, v57
	v_pk_add_f32 v[36:37], v[36:37], v[40:41]
	v_lshlrev_b32_e32 v40, 16, v58
	v_and_b32_e32 v41, 0xffff0000, v58
	v_pk_add_f32 v[32:33], v[32:33], v[42:43]
	v_lshlrev_b32_e32 v42, 16, v59
	v_and_b32_e32 v43, 0xffff0000, v59
	v_pk_add_f32 v[38:39], v[38:39], v[40:41]
	s_waitcnt vmcnt(8)
	v_lshlrev_b32_e32 v40, 16, v60
	v_and_b32_e32 v41, 0xffff0000, v60
	v_pk_add_f32 v[34:35], v[34:35], v[42:43]
	v_lshlrev_b32_e32 v42, 16, v61
	v_and_b32_e32 v43, 0xffff0000, v61
	v_pk_add_f32 v[36:37], v[36:37], v[40:41]
	v_lshlrev_b32_e32 v40, 16, v62
	v_and_b32_e32 v41, 0xffff0000, v62
	v_pk_add_f32 v[32:33], v[32:33], v[42:43]
	v_lshlrev_b32_e32 v42, 16, v63
	v_and_b32_e32 v43, 0xffff0000, v63
	v_pk_add_f32 v[38:39], v[38:39], v[40:41]
	s_waitcnt vmcnt(7)
	v_lshlrev_b32_e32 v40, 16, v68
	v_and_b32_e32 v41, 0xffff0000, v68
	v_pk_add_f32 v[34:35], v[34:35], v[42:43]
	v_lshlrev_b32_e32 v42, 16, v69
	v_and_b32_e32 v43, 0xffff0000, v69
	v_pk_add_f32 v[36:37], v[36:37], v[40:41]
	v_lshlrev_b32_e32 v40, 16, v70
	v_and_b32_e32 v41, 0xffff0000, v70
	v_pk_add_f32 v[32:33], v[32:33], v[42:43]
	v_lshlrev_b32_e32 v42, 16, v71
	v_and_b32_e32 v43, 0xffff0000, v71
	v_pk_add_f32 v[38:39], v[38:39], v[40:41]
	s_waitcnt vmcnt(6)
	v_lshlrev_b32_e32 v40, 16, v72
	v_and_b32_e32 v41, 0xffff0000, v72
	v_pk_add_f32 v[34:35], v[34:35], v[42:43]
	v_lshlrev_b32_e32 v42, 16, v73
	v_and_b32_e32 v43, 0xffff0000, v73
	v_pk_add_f32 v[36:37], v[36:37], v[40:41]
	v_lshlrev_b32_e32 v40, 16, v74
	v_and_b32_e32 v41, 0xffff0000, v74
	v_pk_add_f32 v[32:33], v[32:33], v[42:43]
	v_lshlrev_b32_e32 v42, 16, v75
	v_and_b32_e32 v43, 0xffff0000, v75
	v_pk_add_f32 v[38:39], v[38:39], v[40:41]
	s_waitcnt vmcnt(5)
	v_lshlrev_b32_e32 v40, 16, v26
	v_and_b32_e32 v41, 0xffff0000, v26
	v_lshlrev_b32_e32 v26, 16, v27
	v_and_b32_e32 v27, 0xffff0000, v27
	v_pk_add_f32 v[34:35], v[34:35], v[42:43]
	v_pk_add_f32 v[26:27], v[32:33], v[26:27]
	v_lshlrev_b32_e32 v32, 16, v28
	v_and_b32_e32 v33, 0xffff0000, v28
	v_lshlrev_b32_e32 v28, 16, v29
	v_and_b32_e32 v29, 0xffff0000, v29
	v_pk_add_f32 v[36:37], v[36:37], v[40:41]
	v_pk_add_f32 v[28:29], v[34:35], v[28:29]
	s_waitcnt vmcnt(4)
	v_lshlrev_b32_e32 v34, 16, v22
	v_and_b32_e32 v35, 0xffff0000, v22
	v_lshlrev_b32_e32 v22, 16, v23
	v_and_b32_e32 v23, 0xffff0000, v23
	v_pk_add_f32 v[32:33], v[38:39], v[32:33]
	v_pk_add_f32 v[22:23], v[26:27], v[22:23]
	v_pk_add_f32 v[26:27], v[36:37], v[34:35]
	v_lshlrev_b32_e32 v34, 16, v24
	v_and_b32_e32 v35, 0xffff0000, v24
	v_lshlrev_b32_e32 v24, 16, v25
	v_and_b32_e32 v25, 0xffff0000, v25
	v_pk_add_f32 v[24:25], v[28:29], v[24:25]
	v_pk_add_f32 v[28:29], v[32:33], v[34:35]
	s_waitcnt vmcnt(3)
	v_lshlrev_b32_e32 v32, 16, v18
	v_and_b32_e32 v33, 0xffff0000, v18
	v_lshlrev_b32_e32 v18, 16, v19
	v_and_b32_e32 v19, 0xffff0000, v19
	v_pk_add_f32 v[18:19], v[22:23], v[18:19]
	v_lshlrev_b32_e32 v22, 16, v20
	v_and_b32_e32 v23, 0xffff0000, v20
	v_lshlrev_b32_e32 v20, 16, v21
	v_and_b32_e32 v21, 0xffff0000, v21
	v_pk_add_f32 v[26:27], v[26:27], v[32:33]
	v_pk_add_f32 v[20:21], v[24:25], v[20:21]
	s_waitcnt vmcnt(2)
	v_lshlrev_b32_e32 v24, 16, v14
	v_and_b32_e32 v25, 0xffff0000, v14
	v_lshlrev_b32_e32 v14, 16, v15
	v_and_b32_e32 v15, 0xffff0000, v15
	v_pk_add_f32 v[22:23], v[28:29], v[22:23]
	v_pk_add_f32 v[14:15], v[18:19], v[14:15]
	v_pk_add_f32 v[18:19], v[26:27], v[24:25]
	v_lshlrev_b32_e32 v24, 16, v16
	v_and_b32_e32 v25, 0xffff0000, v16
	v_lshlrev_b32_e32 v16, 16, v17
	v_and_b32_e32 v17, 0xffff0000, v17
	v_pk_add_f32 v[16:17], v[20:21], v[16:17]
	v_pk_add_f32 v[20:21], v[22:23], v[24:25]
	s_waitcnt vmcnt(1)
	v_lshlrev_b32_e32 v22, 16, v10
	v_and_b32_e32 v23, 0xffff0000, v10
	v_lshlrev_b32_e32 v10, 16, v11
	v_and_b32_e32 v11, 0xffff0000, v11
	v_pk_add_f32 v[10:11], v[14:15], v[10:11]
	v_lshlrev_b32_e32 v14, 16, v12
	v_and_b32_e32 v15, 0xffff0000, v12
	v_lshlrev_b32_e32 v12, 16, v13
	v_and_b32_e32 v13, 0xffff0000, v13
	v_pk_add_f32 v[18:19], v[18:19], v[22:23]
	v_pk_add_f32 v[16:17], v[16:17], v[12:13]
	s_waitcnt vmcnt(0)
	v_lshlrev_b32_e32 v12, 16, v6
	v_and_b32_e32 v13, 0xffff0000, v6
	v_lshlrev_b32_e32 v6, 16, v7
	v_and_b32_e32 v7, 0xffff0000, v7
	v_pk_add_f32 v[14:15], v[20:21], v[14:15]
	v_pk_add_f32 v[10:11], v[10:11], v[6:7]
	v_pk_add_f32 v[12:13], v[18:19], v[12:13]
	v_lshlrev_b32_e32 v18, 16, v8
	v_and_b32_e32 v19, 0xffff0000, v8
	v_lshlrev_b32_e32 v6, 16, v9
	v_and_b32_e32 v7, 0xffff0000, v9
	v_pk_add_f32 v[8:9], v[14:15], v[18:19]
	v_mul_f32_e32 v0, v13, v13
	v_mul_f32_e32 v14, v11, v11
	v_fmac_f32_e32 v0, v12, v12
	v_fmac_f32_e32 v14, v10, v10
	v_add_f32_e32 v0, v0, v14
	v_mul_f32_e32 v14, v9, v9
	v_pk_add_f32 v[6:7], v[16:17], v[6:7]
	v_fmac_f32_e32 v14, v8, v8
	v_add_f32_e32 v0, v14, v0
	v_mul_f32_e32 v14, v7, v7
	v_fmac_f32_e32 v14, v6, v6
	v_add_f32_e32 v0, v14, v0
	ds_swizzle_b32 v14, v0 offset:swizzle(SWAP,1)
	v_ashrrev_i32_e32 v18, 6, v205
	s_waitcnt lgkmcnt(0)
	v_add_f32_e32 v0, v0, v14
	ds_swizzle_b32 v14, v0 offset:swizzle(SWAP,2)
	s_waitcnt lgkmcnt(0)
	v_add_f32_e32 v0, v0, v14
	ds_swizzle_b32 v14, v0 offset:swizzle(SWAP,4)
	s_waitcnt lgkmcnt(0)
	v_add_f32_e32 v0, v0, v14
	ds_swizzle_b32 v14, v0 offset:swizzle(SWAP,8)
	s_waitcnt lgkmcnt(0)
	v_add_f32_e32 v0, v0, v14
	ds_swizzle_b32 v14, v0 offset:swizzle(SWAP,16)
	s_waitcnt lgkmcnt(0)
	v_add_f32_e32 v0, v0, v14
	s_nop 0
	v_readlane_b32 s4, v0, 0
	v_readlane_b32 s5, v0, 32
	s_and_saveexec_b64 s[2:3], s[0:1]
	s_nop 0
	v_mov_b32_e32 v0, s5
	v_lshl_add_u32 v14, v18, 2, 0
	v_add_f32_e32 v0, s4, v0
	v_add_u32_e32 v14, 0x14000, v14
	ds_write_b32 v14, v0
	s_or_b64 exec, exec, s[2:3]
	v_mov_b32_e32 v0, s54
	s_waitcnt lgkmcnt(0)
	s_barrier
	ds_read_b128 v[20:23], v0
	v_readlane_b32 s4, v255, 42
	v_readlane_b32 s16, v252, 28
	v_readlane_b32 s28, v252, 40
	v_mov_b32_e32 v19, s4
	s_waitcnt lgkmcnt(0)
	v_add_f32_e32 v0, 0, v20
	v_add_f32_e32 v0, v0, v21
	v_add_f32_e32 v0, v0, v22
	v_add_f32_e32 v0, v0, v23
	ds_read_b128 v[20:23], v19
	v_readlane_b32 s2, v254, 17
	v_readlane_b32 s29, v252, 41
	v_readlane_b32 s3, v254, 18
	s_add_u32 s2, s28, s2
	s_waitcnt lgkmcnt(0)
	v_add_f32_e32 v0, v0, v20
	v_add_f32_e32 v0, v0, v21
	v_add_f32_e32 v0, v0, v22
	v_add_f32_e32 v0, v0, v23
	v_fmamk_f32 v0, v0, 0x39800000, v211
	v_cmp_gt_f32_e32 vcc, s94, v0
	v_mul_f32_e32 v19, 0x4f800000, v0
	s_addc_u32 s3, s29, s3
	v_cndmask_b32_e32 v0, v0, v19, vcc
	v_sqrt_f32_e32 v19, v0
	v_lshl_add_u64 v[24:25], v[66:67], 2, s[2:3]
	v_lshlrev_b32_e32 v14, 16, v2
	v_and_b32_e32 v15, 0xffff0000, v2
	v_add_u32_e32 v20, -1, v19
	v_fma_f32 v21, -v20, v19, v0
	v_cmp_ge_f32_e64 s[4:5], 0, v21
	v_add_u32_e32 v21, 1, v19
	v_lshlrev_b32_e32 v16, 16, v3
	v_cndmask_b32_e64 v20, v19, v20, s[4:5]
	v_fma_f32 v19, -v21, v19, v0
	v_cmp_lt_f32_e64 s[4:5], 0, v19
	v_and_b32_e32 v17, 0xffff0000, v3
	v_lshlrev_b32_e32 v2, 16, v4
	v_cndmask_b32_e64 v19, v20, v21, s[4:5]
	v_mul_f32_e32 v20, 0x37800000, v19
	v_cndmask_b32_e32 v19, v19, v20, vcc
	v_cmp_class_f32_e32 vcc, v0, v212
	v_and_b32_e32 v3, 0xffff0000, v4
	v_lshlrev_b32_e32 v4, 16, v5
	v_cndmask_b32_e32 v0, v19, v0, vcc
	v_div_scale_f32 v19, s[4:5], v0, v0, 1.0
	v_rcp_f32_e32 v20, v19
	v_and_b32_e32 v5, 0xffff0000, v5
	v_readlane_b32 s17, v252, 29
	v_readlane_b32 s18, v252, 30
	v_fma_f32 v21, -v19, v20, 1.0
	v_fmac_f32_e32 v20, v21, v20
	v_div_scale_f32 v21, vcc, 1.0, v0, 1.0
	v_mul_f32_e32 v22, v21, v20
	v_fma_f32 v23, -v19, v22, v21
	v_fmac_f32_e32 v22, v23, v20
	v_fma_f32 v19, -v19, v22, v21
	v_div_fmas_f32 v19, v19, v20, v22
	global_load_dwordx4 v[20:23], v[24:25], off offset:16
	s_nop 0
	global_load_dwordx4 v[24:27], v[24:25], off
	v_div_fixup_f32 v0, v19, v0, 1.0
	v_pk_mul_f32 v[12:13], v[12:13], v[0:1] op_sel_hi:[1,0]
	v_pk_mul_f32 v[10:11], v[10:11], v[0:1] op_sel_hi:[1,0]
	v_pk_mul_f32 v[8:9], v[8:9], v[0:1] op_sel_hi:[1,0]
	v_pk_mul_f32 v[6:7], v[6:7], v[0:1] op_sel_hi:[1,0]
	v_readlane_b32 s19, v252, 31
	v_readlane_b32 s20, v252, 32
	v_readlane_b32 s21, v252, 33
	v_readlane_b32 s22, v252, 34
	v_readlane_b32 s23, v252, 35
	v_readlane_b32 s24, v252, 36
	v_readlane_b32 s25, v252, 37
	v_readlane_b32 s26, v252, 38
	v_readlane_b32 s27, v252, 39
	v_readlane_b32 s30, v252, 42
	v_readlane_b32 s31, v252, 43
	s_waitcnt vmcnt(1)
	v_pk_fma_f32 v[8:9], v[20:21], v[8:9], v[2:3]
	s_waitcnt vmcnt(0)
	v_pk_fma_f32 v[10:11], v[26:27], v[10:11], v[16:17]
	v_pk_fma_f32 v[12:13], v[24:25], v[12:13], v[14:15]
	v_pk_fma_f32 v[6:7], v[22:23], v[6:7], v[4:5]
	v_cvt_pk_bf16_f32 v2, v12, v13
	v_cvt_pk_bf16_f32 v3, v10, v11
	v_cvt_pk_bf16_f32 v4, v8, v9
	v_mul_f32_e32 v0, v13, v13
	v_cvt_pk_bf16_f32 v5, v6, v7
	global_store_dwordx4 v[30:31], v[2:5], off
	v_fmac_f32_e32 v0, v12, v12
	s_nop 0
	v_mul_f32_e32 v2, v11, v11
	v_fmac_f32_e32 v2, v10, v10
	v_add_f32_e32 v0, v0, v2
	v_mul_f32_e32 v2, v9, v9
	v_fmac_f32_e32 v2, v8, v8
	v_add_f32_e32 v0, v2, v0
	v_mul_f32_e32 v2, v7, v7
	v_fmac_f32_e32 v2, v6, v6
	v_add_f32_e32 v0, v2, v0
	ds_swizzle_b32 v2, v0 offset:swizzle(SWAP,1)
	s_waitcnt lgkmcnt(0)
	v_add_f32_e32 v0, v0, v2
	ds_swizzle_b32 v2, v0 offset:swizzle(SWAP,2)
	s_waitcnt lgkmcnt(0)
	v_add_f32_e32 v0, v0, v2
	ds_swizzle_b32 v2, v0 offset:swizzle(SWAP,4)
	s_waitcnt lgkmcnt(0)
	v_add_f32_e32 v0, v0, v2
	ds_swizzle_b32 v2, v0 offset:swizzle(SWAP,8)
	s_waitcnt lgkmcnt(0)
	v_add_f32_e32 v0, v0, v2
	ds_swizzle_b32 v2, v0 offset:swizzle(SWAP,16)
	s_waitcnt lgkmcnt(0)
	v_add_f32_e32 v0, v0, v2
	s_nop 0
	v_readlane_b32 s7, v0, 0
	v_readlane_b32 s8, v0, 32
	s_and_saveexec_b64 s[4:5], s[0:1]
	s_nop 0
	v_mov_b32_e32 v0, s8
	v_add_f32_e32 v0, s7, v0
	v_lshl_add_u32 v2, v18, 2, s54
	ds_write_b32 v2, v0 offset:32
	s_or_b64 exec, exec, s[4:5]
	v_cmp_eq_u32_e32 vcc, 0, v205
	s_waitcnt lgkmcnt(0)
	s_barrier
	s_and_saveexec_b64 s[4:5], vcc
	s_cbranch_execz .LBB0_1239
	v_readlane_b32 s0, v255, 43
	s_nop 1
	v_mov_b32_e32 v0, s0
	ds_read_b128 v[2:5], v0
	v_readlane_b32 s0, v255, 44
	s_waitcnt lgkmcnt(0)
	v_add_f32_e32 v0, 0, v2
	v_add_f32_e32 v0, v0, v3
	v_add_f32_e32 v0, v0, v4
	v_mov_b32_e32 v2, s0
	v_add_f32_e32 v0, v0, v5
	ds_read_b128 v[2:5], v2
	s_waitcnt lgkmcnt(0)
	v_add_f32_e32 v0, v0, v2
	v_add_f32_e32 v0, v0, v3
	v_add_f32_e32 v0, v0, v4
	v_add_f32_e32 v0, v0, v5
	v_fmamk_f32 v0, v0, 0x39800000, v211
	v_cmp_gt_f32_e32 vcc, s94, v0
	v_mul_f32_e32 v2, 0x4f800000, v0
	s_nop 0
	v_cndmask_b32_e32 v0, v0, v2, vcc
	v_sqrt_f32_e32 v2, v0
	s_nop 0
	v_add_u32_e32 v3, -1, v2
	v_fma_f32 v4, -v3, v2, v0
	v_cmp_ge_f32_e64 s[0:1], 0, v4
	v_add_u32_e32 v4, 1, v2
	s_nop 0
	v_cndmask_b32_e64 v3, v2, v3, s[0:1]
	v_fma_f32 v2, -v4, v2, v0
	v_cmp_lt_f32_e64 s[0:1], 0, v2
	s_nop 1
	v_cndmask_b32_e64 v2, v3, v4, s[0:1]
	v_mul_f32_e32 v3, 0x37800000, v2
	v_cndmask_b32_e32 v2, v2, v3, vcc
	v_cmp_class_f32_e32 vcc, v0, v212
	s_nop 1
	v_cndmask_b32_e32 v0, v2, v0, vcc
	v_div_scale_f32 v2, s[0:1], v0, v0, 1.0
	v_rcp_f32_e32 v3, v2
	v_readlane_b32 s0, v254, 9
	v_readlane_b32 s1, v254, 10
	v_fma_f32 v4, -v2, v3, 1.0
	v_fmac_f32_e32 v3, v4, v3
	v_div_scale_f32 v4, vcc, 1.0, v0, 1.0
	v_mul_f32_e32 v5, v4, v3
	v_fma_f32 v6, -v2, v5, v4
	v_fmac_f32_e32 v5, v6, v3
	v_fma_f32 v2, -v2, v5, v4
	v_div_fmas_f32 v2, v2, v3, v5
	v_div_fixup_f32 v0, v2, v0, 1.0
	global_store_dword v1, v0, s[0:1]
